# phase 2: first K chunk of the next tile prefetched during the selection (into v86-v117), next to the Q/W prefetch
# baseline (speedup 1.0000x reference)
; __device__ void phase2(const Params& p, unsigned char* smem) {
;   u16 (*sc)[8192] = (u16 (*)[8192])smem;
;   unsigned char* ws = p.ws;
;   const int tid = threadIdx.x, lane = tid & 63, wave = tid >> 6;
;   const int NTILE = 4096 + 64;
;   for (int it = blockIdx.x; it < NTILE; it += gridDim.x) {
;     const int rr = it >> 8, ww = it & 255;
;     const int idx = (rr & 1) ? (rr << 8) + 255 - ww : it;
;     int tok0, nvis; const u16* KI; u64* mrow0; int mld;
;     if (idx < 4096) {
;       int b = idx & 3, j8 = 1023 - (idx >> 2);
;       int q0 = j8 * 8;
;       tok0 = b * 8192 + q0; nvis = ((q0 >> 6) + 1) * 64;
;       KI = (const u16*)(ws + OFF_KIP) + (size_t)b * 8192 * 64;
;       mrow0 = (u64*)(ws + OFF_MASKP) + (size_t)tok0 * 128; mld = 128;
;     } else {
;       int s = idx - 4096; int b = s >> 3, q0 = (s & 7) * 8;
;       tok0 = NPROMPT + b * 64 + q0; nvis = 1088;
;       KI = (const u16*)(ws + OFF_KIS) + (size_t)b * 1088 * 64;
;       mrow0 = (u64*)(ws + OFF_MASKS) + (size_t)(b * 64 + q0) * 32; mld = 32;
;     }
;     const int nv512 = (nvis + 511) >> 9;
;     {
;       const int tail = nv512 * 512 - nvis;
;       for (int e = tid; e < 8 * tail; e += 512) { int q = e / tail, k = e % tail; sc[q][nvis + k] = 0; }
;     }
;     const u16* QI = (const u16*)(ws + OFF_QI);
;     const float* WI = (const float*)(ws + OFF_WI);
;     const int n16 = lane & 15, g4 = lane >> 4;
.LBB0_524:
	s_cmp_gt_i32 s90, 2
	s_cselect_b64 s[0:1], -1, 0
	s_cmp_lt_i32 s91, 2
	s_cselect_b64 s[4:5], -1, 0
	s_or_b64 s[0:1], s[0:1], s[4:5]
	s_and_b64 vcc, exec, s[0:1]
	s_cbranch_vccnz .LBB0_608
	s_cmpk_gt_i32 s94, 0x103f
	v_and_b32_e32 v2, 0x3ff, v0
	s_cbranch_scc1 .LBB0_596
	v_lshlrev_b32_e32 v1, 7, v2
	s_waitcnt vmcnt(0)
	v_lshrrev_b32_e32 v133, 6, v2
	v_and_b32_e32 v118, 0x380, v1
	v_mov_b32_e32 v119, 0
	s_add_u32 s0, s88, 0x19aa4800
	v_and_b32_e32 v9, 15, v2
	v_lshl_add_u64 v[4:5], s[88:89], 0, v[118:119]
	v_and_b32_e32 v118, 48, v2
	v_bfe_u32 v145, v2, 5, 1
	v_lshlrev_b32_e32 v11, 7, v133
	s_addc_u32 s1, s89, 0
	v_lshrrev_b32_e32 v1, 1, v2
	v_lshl_add_u64 v[4:5], v[4:5], 0, v[118:119]
	s_mov_b64 s[6:7], 0xa220800
	v_lshl_or_b32 v11, v145, 14, v11
	v_lshlrev_b32_e32 v12, 1, v9
	s_mov_b32 s37, 0x10000
	v_and_b32_e32 v7, 63, v2
	s_add_u32 s3, s88, 0x196a4800
	v_and_b32_e32 v6, 24, v1
	v_lshl_add_u64 v[120:121], v[4:5], 0, s[6:7]
	v_and_b32_e32 v4, 16, v2
	v_mov_b32_e32 v5, v119
	v_lshlrev_b32_e32 v8, 6, v9
	v_mov_b32_e32 v1, 0x20000
	v_or3_b32 v151, v11, v12, s37
	v_lshlrev_b32_e32 v11, 13, v133
	v_lshlrev_b32_e32 v9, 7, v9
	s_addc_u32 s33, s89, 0
	v_lshl_add_u64 v[4:5], s[88:89], 0, v[4:5]
	s_mov_b64 s[6:7], 0x144a0800
	v_lshl_or_b32 v147, v133, 10, v1
	v_lshlrev_b32_e32 v149, 4, v7
	v_or3_b32 v118, v11, v9, v118
	s_mov_b64 s[60:61], 0x10000
	v_lshlrev_b32_e32 v138, 1, v6
	v_mbcnt_lo_u32_b32 v6, -1, 0
	s_mov_b64 s[4:5], src_shared_base
	v_lshl_add_u64 v[122:123], v[4:5], 0, s[6:7]
	v_lshlrev_b32_e32 v10, 12, v133
	v_lshlrev_b32_e32 v146, 14, v133
	v_or_b32_e32 v124, v147, v149
	v_lshlrev_b64 v[4:5], v2, -1
	s_add_u32 s56, s92, 0xc0
	s_movk_i32 s36, 0x400
	v_lshl_add_u64 v[134:135], v[118:119], 0, s[60:61]
	v_lshlrev_b32_e32 v118, 3, v7
	v_mbcnt_hi_u32_b32 v154, -1, v6
	v_mov_b32_e32 v6, 0x80
	v_bfe_u32 v144, v2, 3, 1
	v_lshlrev_b32_e32 v148, 2, v7
	v_mov_b32_e32 v125, s5
	v_or_b32_e32 v126, 4, v124
	v_mov_b32_e32 v127, s5
	v_or_b32_e32 v128, 8, v124
	v_mov_b32_e32 v129, s5
	v_or_b32_e32 v130, 12, v124
	v_mov_b32_e32 v131, s5
	v_not_b32_e32 v1, v5
	v_not_b32_e32 v132, v4
	v_cmp_gt_u32_e64 s[4:5], 8, v7
	s_addc_u32 s57, s93, 0
	v_cmp_eq_u32_e64 s[6:7], 63, v7
	v_cmp_gt_u32_e64 s[8:9], 62, v7
	v_cmp_gt_u32_e64 s[10:11], 60, v7
	v_cmp_gt_u32_e64 s[12:13], 56, v7
	v_cmp_gt_u32_e64 s[14:15], 48, v7
	v_cmp_gt_u32_e64 s[16:17], 32, v7
	s_mov_b32 s59, 0
	v_cmp_eq_u32_e64 s[18:19], 0, v7
	v_cmp_eq_u32_e64 s[20:21], 1, v7
	v_cmp_eq_u32_e64 s[22:23], 2, v7
	v_cmp_eq_u32_e64 s[24:25], 3, v7
	v_cmp_eq_u32_e64 s[26:27], 4, v7
	v_cmp_eq_u32_e64 s[28:29], 5, v7
	v_cmp_eq_u32_e64 s[30:31], 6, v7
	v_cmp_eq_u32_e64 s[34:35], 7, v7
	v_not_b32_e32 v150, v2
	v_add_u32_e32 v5, 0x600, v2
	v_or_b32_e32 v4, 0x400, v2
	v_add_u32_e32 v3, 0x200, v2
	v_or3_b32 v152, v146, v149, s36
	v_lshl_add_u64 v[136:137], s[88:89], 0, v[118:119]
	s_movk_i32 s68, 0x100
	s_movk_i32 s69, 0xff
	s_movk_i32 s70, 0x5ff
	v_lshlrev_b32_e32 v118, 1, v8
	v_lshlrev_b32_e32 v140, 1, v10
	s_movk_i32 s71, 0x8000
	v_mov_b32_e32 v153, 1
	v_mov_b32_e32 v156, v119
	v_mov_b32_e32 v157, v119
	v_mov_b32_e32 v158, v119
	v_mov_b32_e32 v159, v119
	v_lshl_or_b32 v155, v154, 2, v6
	s_mov_b32 s72, s94
	s_mov_b32 s97, 0
	s_mov_b32 s55, 0
	s_branch .LBB0_528

; __device__ void phase2(const Params& p, unsigned char* smem) {
;     ...
;       const int nchunk = nvis >> 6;
;       const u16* kbase = KI + (size_t)n16 * 64 + 8 * g4;
;       bf16x8 nA0, nB0, nA1, nB1, nA2, nB2, nA3, nB3;
;       int c = wave;
;       if (c < nchunk) P2_LOADCHUNK(c, nA0, nB0, nA1, nB1, nA2, nB2, nA3, nB3)
.Lq_skip:
	s_lshr_b32 s47, s74, 6
	v_cmp_gt_u32_e64 s[36:37], s47, v133
	s_and_saveexec_b64 s[38:39], s[36:37]
	s_cbranch_execz .LBB0_548
	s_cmp_lg_u32 s55, 0
	s_cbranch_scc1 .LBB0_548
	v_lshl_add_u64 v[6:7], s[48:49], 0, v[118:119]
	v_mov_b32_e32 v139, v119
	v_lshl_add_u64 v[6:7], v[6:7], 0, v[138:139]
	v_mov_b32_e32 v141, v119
	v_lshl_add_u64 v[6:7], v[6:7], 0, v[140:141]
	global_load_dwordx4 v[34:37], v[6:7], off
	global_load_dwordx4 v[30:33], v[6:7], off offset:64
	global_load_dwordx4 v[26:29], v[6:7], off offset:2048
	global_load_dwordx4 v[22:25], v[6:7], off offset:2112
	v_add_co_u32_e32 v6, vcc, 0x1000, v6
	s_nop 1
	v_addc_co_u32_e32 v7, vcc, 0, v7, vcc
	global_load_dwordx4 v[18:21], v[6:7], off
	global_load_dwordx4 v[14:17], v[6:7], off offset:64
	global_load_dwordx4 v[10:13], v[6:7], off offset:2048
	s_nop 0
	global_load_dwordx4 v[6:9], v[6:7], off offset:2112
.LBB0_548:
	s_or_b64 exec, exec, s[38:39]
	s_and_saveexec_b64 s[38:39], s[36:37]
	s_cbranch_execz .LBB0_554
	s_waitcnt vmcnt(0)
	s_cmp_lg_u32 s55, 0
	s_cbranch_scc0 .Lk_nocopy
	v_mov_b32_e32 v34, v86
	v_mov_b32_e32 v35, v87
	v_mov_b32_e32 v36, v88
	v_mov_b32_e32 v37, v89
	v_mov_b32_e32 v30, v90
	v_mov_b32_e32 v31, v91
	v_mov_b32_e32 v32, v92
	v_mov_b32_e32 v33, v93
	v_mov_b32_e32 v26, v94
	v_mov_b32_e32 v27, v95
	v_mov_b32_e32 v28, v96
	v_mov_b32_e32 v29, v97
	v_mov_b32_e32 v22, v98
	v_mov_b32_e32 v23, v99
	v_mov_b32_e32 v24, v100
	v_mov_b32_e32 v25, v101
	v_mov_b32_e32 v18, v102
	v_mov_b32_e32 v19, v103
	v_mov_b32_e32 v20, v104
	v_mov_b32_e32 v21, v105
	v_mov_b32_e32 v14, v106
	v_mov_b32_e32 v15, v107
	v_mov_b32_e32 v16, v108
	v_mov_b32_e32 v17, v109
	v_mov_b32_e32 v10, v110
	v_mov_b32_e32 v11, v111
	v_mov_b32_e32 v12, v112
	v_mov_b32_e32 v13, v113
	v_mov_b32_e32 v6, v114
	v_mov_b32_e32 v7, v115
	v_mov_b32_e32 v8, v116
	v_mov_b32_e32 v9, v117
	s_mov_b32 s55, 0
.Lk_nocopy:
	v_readfirstlane_b32 s40, v133
	v_lshl_add_u64 v[142:143], s[48:49], 0, v[134:135]
	v_lshrrev_b32_e32 v202, 4, v154
	v_and_b32_e32 v203, 1, v202
	v_lshrrev_b32_e32 v204, 1, v202
	v_lshl_or_b32 v203, v203, 1, v204
	v_lshlrev_b32_e32 v203, 14, v203
	v_and_b32_e32 v204, 15, v154
	v_lshl_or_b32 v210, v204, 1, v203
	v_lshl_add_u32 v210, v133, 7, v210
	v_add_co_u32_e32 v208, vcc, 0x1000, v142
	v_add_u32_e32 v211, 0x10000, v210
	v_addc_co_u32_e32 v209, vcc, 0, v143, vcc
	s_add_i32 s41, s40, 8

; __device__ void phase2(const Params& p, unsigned char* smem) {
;     ...
;   for (int it = blockIdx.x; it < NTILE; it += gridDim.x) {
;     const int rr = it >> 8, ww = it & 255;
;     const int idx = (rr & 1) ? (rr << 8) + 255 - ww : it;
;     int tok0, nvis; const u16* KI; u64* mrow0; int mld;
;     if (idx < 4096) {
;       int b = idx & 3, j8 = 1023 - (idx >> 2);
;       int q0 = j8 * 8;
;       tok0 = b * 8192 + q0; nvis = ((q0 >> 6) + 1) * 64;
;       KI = (const u16*)(ws + OFF_KIP) + (size_t)b * 8192 * 64;
;       mrow0 = (u64*)(ws + OFF_MASKP) + (size_t)tok0 * 128; mld = 128;
;     } else {
;       int s = idx - 4096; int b = s >> 3, q0 = (s & 7) * 8;
;       tok0 = NPROMPT + b * 64 + q0; nvis = 1088;
;       KI = (const u16*)(ws + OFF_KIS) + (size_t)b * 1088 * 64;
;       mrow0 = (u64*)(ws + OFF_MASKS) + (size_t)(b * 64 + q0) * 32; mld = 32;
;     }
;     const int nv512 = (nvis + 511) >> 9;
;     ...
;     const u16* QI = (const u16*)(ws + OFF_QI);
;     const float* WI = (const float*)(ws + OFF_WI);
;     const int n16 = lane & 15, g4 = lane >> 4;
;     bf16x8 qa[4][2]; float4 wv[4];
; #pragma unroll
;     for (int pp = 0; pp < 4; pp++) {
;       const int ql = 2 * pp + (n16 >> 3), hh = n16 & 7;
; #pragma unroll
;       for (int kh = 0; kh < 2; kh++)
;         qa[pp][kh] = as_bf8(*(const uint4*)(QI + (size_t)(tok0 + ql) * 512 + hh * 64 + kh * 32 + 8 * g4));
;       wv[pp] = *(const float4*)(WI + (size_t)(tok0 + 2 * pp + (g4 >> 1)) * 8 + 4 * (g4 & 1));
;     }
;     ...
;       const int nchunk = nvis >> 6;
;       const u16* kbase = KI + (size_t)n16 * 64 + 8 * g4;
;       bf16x8 nA0, nB0, nA1, nB1, nA2, nB2, nA3, nB3;
;       int c = wave;
;       if (c < nchunk) P2_LOADCHUNK(c, nA0, nB0, nA1, nB1, nA2, nB2, nA3, nB3)
.LBB0_554:
	s_or_b64 exec, exec, s[38:39]
	s_waitcnt vmcnt(0)
	s_waitcnt lgkmcnt(0)
	s_barrier
	s_load_dword s96, s[56:57], 0x0
	s_mov_b32 s97, 0
	s_mov_b32 s55, 0
	s_waitcnt lgkmcnt(0)
	s_add_i32 s96, s96, s72
	s_cmpk_gt_i32 s96, 0x103f
	s_cbranch_scc1 .Lq_nopf
	s_and_b32 s36, s96, 0x100
	s_xor_b32 s37, s96, 0xff
	s_cmp_eq_u32 s36, 0
	s_cselect_b32 s38, s96, s37
	s_cmpk_gt_i32 s38, 0xfff
	s_cbranch_scc1 .Lq_sample
	s_lshl_b32 s37, s38, 1
	s_and_b32 s36, s38, 3
	s_and_b32 s37, s37, -8
	s_sub_i32 s37, 0x1ff8, s37
	s_andn2_b32 s52, s37, 63
	s_add_i32 s52, s52, 64
	s_and_b32 s53, s38, 3
	s_lshl_b32 s53, s53, 20
	s_add_u32 s50, s3, s53
	s_addc_u32 s51, s33, 0
	s_lshl_b32 s36, s36, 13
	s_add_i32 s95, s37, s36
	s_branch .Lq_issue
.Lq_sample:
	s_add_i32 s36, s38, 0xfffff000
	s_lshr_b32 s36, s36, 3
	s_mul_i32 s53, s36, 0x22000
	s_add_u32 s50, s0, s53
	s_addc_u32 s51, s1, 0
	s_movk_i32 s52, 0x440
	s_lshl_b32 s37, s38, 3
	s_and_b32 s37, s37, 56
	s_lshl_b32 s36, s36, 6
	s_or_b32 s36, s36, s37
	s_add_i32 s95, s36, 0x8000
.Lq_issue:
	v_add_u32_e32 v70, s95, v144
	v_add_u32_e32 v78, s95, v145
	v_ashrrev_i32_e32 v71, 31, v70
	v_ashrrev_i32_e32 v79, 31, v78
	v_lshlrev_b64 v[38:39], 10, v[70:71]
	v_lshlrev_b64 v[46:47], 5, v[78:79]
	v_add_u32_e32 v48, 2, v70
	v_add_u32_e32 v56, 2, v78
	v_add_u32_e32 v62, 4, v70
	v_add_u32_e32 v72, 4, v78
	v_add_u32_e32 v70, 6, v70
	v_add_u32_e32 v78, 6, v78
	v_ashrrev_i32_e32 v49, 31, v48
	v_ashrrev_i32_e32 v57, 31, v56
	v_ashrrev_i32_e32 v63, 31, v62
	v_ashrrev_i32_e32 v73, 31, v72
	v_ashrrev_i32_e32 v71, 31, v70
	v_ashrrev_i32_e32 v79, 31, v78
	v_lshlrev_b64 v[48:49], 10, v[48:49]
	v_lshlrev_b64 v[56:57], 5, v[56:57]
	v_lshlrev_b64 v[62:63], 10, v[62:63]
	v_lshlrev_b64 v[72:73], 5, v[72:73]
	v_lshlrev_b64 v[70:71], 10, v[70:71]
	v_lshlrev_b64 v[78:79], 5, v[78:79]
	v_lshl_add_u64 v[42:43], v[120:121], 0, v[38:39]
	v_lshl_add_u64 v[46:47], v[122:123], 0, v[46:47]
	v_lshl_add_u64 v[54:55], v[120:121], 0, v[48:49]
	v_lshl_add_u64 v[58:59], v[122:123], 0, v[56:57]
	v_lshl_add_u64 v[66:67], v[120:121], 0, v[62:63]
	v_lshl_add_u64 v[72:73], v[122:123], 0, v[72:73]
	v_lshl_add_u64 v[80:81], v[120:121], 0, v[70:71]
	v_lshl_add_u64 v[82:83], v[122:123], 0, v[78:79]
	global_load_dwordx4 v[38:41], v[42:43], off
	s_nop 0
	global_load_dwordx4 v[42:45], v[42:43], off offset:64
	s_nop 0
	global_load_dwordx4 v[46:49], v[46:47], off
	s_nop 0
	global_load_dwordx4 v[50:53], v[54:55], off
	s_nop 0
	global_load_dwordx4 v[54:57], v[54:55], off offset:64
	s_nop 0
	global_load_dwordx4 v[58:61], v[58:59], off
	s_nop 0
	global_load_dwordx4 v[62:65], v[66:67], off
	s_nop 0
	global_load_dwordx4 v[66:69], v[66:67], off offset:64
	s_nop 0
	global_load_dwordx4 v[70:73], v[72:73], off
	s_nop 0
	global_load_dwordx4 v[74:77], v[80:81], off
	s_nop 0
	global_load_dwordx4 v[78:81], v[80:81], off offset:64
	s_nop 0
	global_load_dwordx4 v[82:85], v[82:83], off
	v_readfirstlane_b32 s53, v133
	s_lshr_b32 s54, s52, 6
	s_cmp_lt_u32 s53, s54
	s_cbranch_scc0 .Lq_nok
	v_lshl_add_u64 v[160:161], s[50:51], 0, v[118:119]
	v_mov_b32_e32 v163, v119
	v_mov_b32_e32 v162, v138
	v_lshl_add_u64 v[160:161], v[160:161], 0, v[162:163]
	v_mov_b32_e32 v162, v140
	v_lshl_add_u64 v[160:161], v[160:161], 0, v[162:163]
	global_load_dwordx4 v[86:89], v[160:161], off
	global_load_dwordx4 v[90:93], v[160:161], off offset:64
	global_load_dwordx4 v[94:97], v[160:161], off offset:2048
	global_load_dwordx4 v[98:101], v[160:161], off offset:2112
	s_mov_b64 s[36:37], 0x1000
	v_lshl_add_u64 v[160:161], v[160:161], 0, s[36:37]
	global_load_dwordx4 v[102:105], v[160:161], off
	global_load_dwordx4 v[106:109], v[160:161], off offset:64
	global_load_dwordx4 v[110:113], v[160:161], off offset:2048
	global_load_dwordx4 v[114:117], v[160:161], off offset:2112
	s_mov_b32 s55, 1
.Lq_nok:
	s_mov_b32 s97, 1
